# v2 + RWKV S1 phase units re-dealt so every workgroup does exactly 48 K-tiles (c<160: 3 units stride 160; c>=160: 1 unit + the K=2048 unit)
# speedup vs baseline: 1.0191x; 1.0061x over previous
.LBB0_1160:
	s_cmp_eq_u32 s85, 7
	s_cbranch_scc0 .Lmy_s1_norestore
	v_readlane_b32 s2, v254, 34
	s_movk_i32 s50, 0x100
	s_lshr_b32 s2, s2, 3
	s_lshr_b32 vcc_lo, s2, 3
	v_writelane_b32 v252, vcc_lo, 40
	s_and_b32 vcc_lo, s2, 7
	v_writelane_b32 v252, vcc_lo, 43

.LBB0_1171:
	s_cmp_eq_u32 s85, 7
	s_cbranch_scc0 .Lmy_s1_skip
	v_readlane_b32 s5, v254, 34
	s_lshr_b32 s5, s5, 3
	s_cmpk_lt_u32 s5, 0xa0
	s_cbranch_scc0 .Lmy_s1_hi
	s_add_i32 s2, s5, 0x60
	s_movk_i32 s50, 0xa0
	s_branch .Lmy_s1_setlanes
.Lmy_s1_hi:
	s_sub_i32 s2, s5, 0xa0
	s_movk_i32 s50, 0x400
.Lmy_s1_setlanes:
	s_lshr_b32 vcc_lo, s2, 3
	v_writelane_b32 v252, vcc_lo, 40
	s_and_b32 vcc_lo, s2, 7
	v_writelane_b32 v252, vcc_lo, 43
